# attention: the 512 sample queries are processed by waves 0-1 of every workgroup instead of a 17th iteration of 64 workgroups
# speedup vs baseline: 1.0096x; 1.0096x over previous
; template <class T> __device__ __forceinline__ T launder(T p) { asm volatile("" : "+s"(p)); return p; }
; __device__ __forceinline__ int otid() { int t = threadIdx.x; asm volatile("" : "+v"(t)); return t; }
; __device__ __forceinline__ void phase_attn(KP kp, int l, unsigned char* shm) {
;   kp = launder(kp);
;   const int tid = otid(), lane = tid & 63, w = __builtin_amdgcn_readfirstlane(tid >> 6);
;   unsigned char* ws = kp->ws;
;   unsigned char* tileb = shm + w * 5120;
;   unsigned short* selw = (unsigned short*)(shm + w * 5120 + 4608);
;   const unsigned tr_addr = (unsigned)(size_t)tileb + (unsigned)((4 * (lane >> 4) + ((lane & 15) >> 2)) * 144 + (lane & 3) * 8);
;   bf16_t* Q = (bf16_t*)(ws + W_Q);
;   const unsigned short* SEL = (const unsigned short*)(ws + W_SEL);
;   const int nn = lane & 15, kg = lane >> 4;
;   const int ks8 = lane >> 3, dc = lane & 7;
;   for (int q = blockIdx.x * 8 + w; q < MT; q += gridDim.x * 8) {
;     int r = q;
;     if (gridDim.x == 256 && q < MP) r = ((q >> 3) & 7) * 4096 + (q >> 11) * 256 + ((q >> 6) & 31) * 8 + (q & 7);
.LBB0_3447:
	s_or_b64 exec, exec, s[0:1]
	v_readlane_b32 s0, v254, 2
	v_readlane_b32 s1, v254, 3
	s_waitcnt lgkmcnt(0)
	s_barrier
	v_readlane_b32 s2, v254, 15
	v_readlane_b32 s4, v255, 8
	v_readlane_b32 s3, v255, 24
	v_readlane_b32 s5, v254, 51
	v_readfirstlane_b32 s6, v244
	s_load_dwordx2 s[0:1], s[0:1], 0xb0
	s_lshr_b32 s6, s6, 6
	s_add_i32 s2, s2, s6
	s_cmp_lt_i32 s2, 0x8200
	s_cbranch_scc0 .LBB0_3464
	s_mov_b32 s56, s6
	v_readlane_b32 s57, v254, 6
	s_mul_i32 s46, s6, 0x4400
	s_add_i32 s47, s46, 0x1000
	s_add_i32 s48, s46, 0x2000
	s_add_i32 s49, s46, 0x3000
	s_add_i32 s52, s46, 0x4000
	v_and_b32_e32 v211, 15, v252
	v_lshrrev_b32_e32 v212, 4, v252
	v_and_b32_e32 v213, 7, v252
	v_lshlrev_b32_e32 v197, 1, v212
	v_xor_b32_e32 v197, v197, v213
	v_lshlrev_b32_e32 v197, 4, v197
	v_add_u32_e32 v193, 0x1000, v197
	v_add_u32_e32 v194, 0xc00, v197
	v_add_u32_e32 v195, 0x800, v197
	v_add_u32_e32 v196, 0x400, v197
	v_bfe_u32 v213, v211, 1, 2
	v_lshlrev_b32_e32 v213, 1, v213
	v_xor_b32_e32 v213, v213, v212
	v_lshlrev_b32_e32 v213, 4, v213
	v_lshl_add_u32 v213, v211, 7, v213
	v_add_u32_e32 v180, s46, v213
	v_xor_b32_e32 v181, 64, v180
	v_lshrrev_b32_e32 v214, 2, v211
	v_lshl_add_u32 v214, v212, 2, v214
	v_bfe_u32 v215, v214, 1, 2
	v_bfe_u32 v216, v211, 1, 1
	v_and_b32_e32 v217, 1, v211
	v_lshlrev_b32_e32 v217, 3, v217
	v_lshl_add_u32 v218, v214, 7, v217
	v_lshl_add_u32 v218, v216, 4, v218
	v_add_u32_e32 v218, s46, v218
	v_xor_b32_e32 v197, 0, v215
	v_lshl_add_u32 v182, v197, 5, v218
	v_xor_b32_e32 v197, 1, v215
	v_lshl_add_u32 v183, v197, 5, v218
	v_xor_b32_e32 v197, 2, v215
	v_lshl_add_u32 v184, v197, 5, v218
	v_xor_b32_e32 v197, 3, v215
	v_lshl_add_u32 v185, v197, 5, v218
	v_lshlrev_b32_e32 v188, 3, v252
	v_add_u32_e32 v186, s52, v188
	v_lshrrev_b32_e32 v197, 3, v252
	v_lshl_add_u32 v187, v197, 1, s52
	v_lshlrev_b32_e32 v189, 7, v211
	v_lshl_add_u32 v189, v212, 4, v189
	v_lshlrev_b32_e32 v190, 7, v211
	v_lshl_add_u32 v190, v212, 3, v190
	v_xor_b32_e32 v197, 16, v252
	v_lshlrev_b32_e32 v191, 2, v197
	v_xor_b32_e32 v197, 32, v252
	v_lshlrev_b32_e32 v192, 2, v197
	v_cmp_gt_u32_e64 s[42:43], 4, v211
	v_mov_b32_e32 v144, 0
	v_mov_b32_e32 v145, 0
	v_mov_b32_e32 v146, 0
	v_mov_b32_e32 v147, 0
	v_mov_b32_e32 v148, 0
	v_mov_b32_e32 v149, 0
	v_mov_b32_e32 v150, 0
	v_mov_b32_e32 v151, 0
	v_mov_b32_e32 v152, 0
	v_mov_b32_e32 v153, 0
	v_mov_b32_e32 v154, 0
	v_mov_b32_e32 v155, 0
	v_mov_b32_e32 v156, 0
	v_mov_b32_e32 v157, 0
	v_mov_b32_e32 v158, 0
	v_mov_b32_e32 v159, 0
	s_waitcnt lgkmcnt(0)
	s_mov_b32 s51, s2
	s_cmp_lg_u32 s5, 0
	s_cbranch_scc1 .Lattn_noswz_1
	s_cmp_ge_i32 s2, 0x8000
	s_cbranch_scc1 .Lattn_noswz_1
	s_lshl_b32 s6, s2, 9
	s_and_b32 s6, s6, 0x7000
	s_lshr_b32 s7, s2, 3
	s_and_b32 s8, s7, 0xffffff00
	s_and_b32 s7, s7, 0xf8
	s_or_b32 s6, s6, s8
	s_or_b32 s6, s6, s7
	s_and_b32 s7, s2, 7
	s_or_b32 s51, s6, s7

; __device__ __forceinline__ void phase_attn(KP kp, int l, unsigned char* shm) {
;     ...
;       float mx = -1e30f;
; #pragma unroll
;       for (int kb = 0; kb < 16; ++kb)
; #pragma unroll
;         for (int j = 0; j < 4; ++j) {
;           const int key = kb * 16 + kg * 4 + j;
;           lg[kb][j] = key < cnt ? lg[kb][j] : -1e30f;
;           mx = fmaxf(mx, lg[kb][j]);
;         }
;       mx = fmaxf(mx, __shfl_xor(mx, 16));
;       mx = fmaxf(mx, __shfl_xor(mx, 32));
;       float sum = 0.f;
; #pragma unroll
;       for (int kb = 0; kb < 16; ++kb)
; #pragma unroll
;         for (int j = 0; j < 4; ++j) { lg[kb][j] = __builtin_amdgcn_exp2f(lg[kb][j] - mx); sum += lg[kb][j]; }
;       sum += __shfl_xor(sum, 16);
;       sum += __shfl_xor(sum, 32);
.Lattn_nomask_4:
	v_max3_f32 v176, v32, v33, v34
	v_max3_f32 v176, v176, v35, v36
	v_max3_f32 v176, v176, v37, v38
	v_max3_f32 v176, v176, v39, v40
	v_max3_f32 v176, v176, v41, v42
	v_max3_f32 v176, v176, v43, v44
	v_max3_f32 v176, v176, v45, v46
	v_max3_f32 v176, v176, v47, v48
	v_max3_f32 v176, v176, v49, v50
	v_max3_f32 v176, v176, v51, v52
	v_max3_f32 v176, v176, v53, v54
	v_max3_f32 v176, v176, v55, v56
	v_max3_f32 v176, v176, v57, v58
	v_max3_f32 v176, v176, v59, v60
	v_max3_f32 v176, v176, v61, v62
	v_max3_f32 v176, v176, v63, v64
	v_max3_f32 v176, v176, v65, v66
	v_max3_f32 v176, v176, v67, v68
	v_max3_f32 v176, v176, v69, v70
	v_max3_f32 v176, v176, v71, v72
	v_max3_f32 v176, v176, v73, v74
	v_max3_f32 v176, v176, v75, v76
	v_max3_f32 v176, v176, v77, v78
	v_max3_f32 v176, v176, v79, v80
	v_max3_f32 v176, v176, v81, v82
	v_max3_f32 v176, v176, v83, v84
	v_max3_f32 v176, v176, v85, v86
	v_max3_f32 v176, v176, v87, v88
	v_max3_f32 v176, v176, v89, v90
	v_max3_f32 v176, v176, v91, v92
	v_max3_f32 v176, v176, v93, v94
	v_max_f32_e32 v176, v176, v95
	ds_bpermute_b32 v197, v191, v176
	s_waitcnt lgkmcnt(0)
	v_max_f32_e32 v176, v176, v197
	ds_bpermute_b32 v197, v192, v176
	s_waitcnt lgkmcnt(0)
	v_max_f32_e32 v176, v176, v197
	v_mov_b32_e32 v177, v176
	v_pk_add_f32 v[32:33], v[32:33], v[176:177] neg_lo:[0,1] neg_hi:[0,1]
	v_pk_add_f32 v[34:35], v[34:35], v[176:177] neg_lo:[0,1] neg_hi:[0,1]
	v_pk_add_f32 v[36:37], v[36:37], v[176:177] neg_lo:[0,1] neg_hi:[0,1]
	v_pk_add_f32 v[38:39], v[38:39], v[176:177] neg_lo:[0,1] neg_hi:[0,1]
	v_pk_add_f32 v[40:41], v[40:41], v[176:177] neg_lo:[0,1] neg_hi:[0,1]
	v_pk_add_f32 v[42:43], v[42:43], v[176:177] neg_lo:[0,1] neg_hi:[0,1]
	v_pk_add_f32 v[44:45], v[44:45], v[176:177] neg_lo:[0,1] neg_hi:[0,1]
	v_pk_add_f32 v[46:47], v[46:47], v[176:177] neg_lo:[0,1] neg_hi:[0,1]
	v_pk_add_f32 v[48:49], v[48:49], v[176:177] neg_lo:[0,1] neg_hi:[0,1]
	v_pk_add_f32 v[50:51], v[50:51], v[176:177] neg_lo:[0,1] neg_hi:[0,1]
	v_pk_add_f32 v[52:53], v[52:53], v[176:177] neg_lo:[0,1] neg_hi:[0,1]
	v_pk_add_f32 v[54:55], v[54:55], v[176:177] neg_lo:[0,1] neg_hi:[0,1]
	v_pk_add_f32 v[56:57], v[56:57], v[176:177] neg_lo:[0,1] neg_hi:[0,1]
	v_pk_add_f32 v[58:59], v[58:59], v[176:177] neg_lo:[0,1] neg_hi:[0,1]
	v_pk_add_f32 v[60:61], v[60:61], v[176:177] neg_lo:[0,1] neg_hi:[0,1]
	v_pk_add_f32 v[62:63], v[62:63], v[176:177] neg_lo:[0,1] neg_hi:[0,1]
	v_pk_add_f32 v[64:65], v[64:65], v[176:177] neg_lo:[0,1] neg_hi:[0,1]
	v_pk_add_f32 v[66:67], v[66:67], v[176:177] neg_lo:[0,1] neg_hi:[0,1]
	v_pk_add_f32 v[68:69], v[68:69], v[176:177] neg_lo:[0,1] neg_hi:[0,1]
	v_pk_add_f32 v[70:71], v[70:71], v[176:177] neg_lo:[0,1] neg_hi:[0,1]
	v_pk_add_f32 v[72:73], v[72:73], v[176:177] neg_lo:[0,1] neg_hi:[0,1]
	v_pk_add_f32 v[74:75], v[74:75], v[176:177] neg_lo:[0,1] neg_hi:[0,1]
	v_pk_add_f32 v[76:77], v[76:77], v[176:177] neg_lo:[0,1] neg_hi:[0,1]
	v_pk_add_f32 v[78:79], v[78:79], v[176:177] neg_lo:[0,1] neg_hi:[0,1]
	v_pk_add_f32 v[80:81], v[80:81], v[176:177] neg_lo:[0,1] neg_hi:[0,1]
	v_pk_add_f32 v[82:83], v[82:83], v[176:177] neg_lo:[0,1] neg_hi:[0,1]
	v_pk_add_f32 v[84:85], v[84:85], v[176:177] neg_lo:[0,1] neg_hi:[0,1]
	v_pk_add_f32 v[86:87], v[86:87], v[176:177] neg_lo:[0,1] neg_hi:[0,1]
	v_pk_add_f32 v[88:89], v[88:89], v[176:177] neg_lo:[0,1] neg_hi:[0,1]
	v_pk_add_f32 v[90:91], v[90:91], v[176:177] neg_lo:[0,1] neg_hi:[0,1]
	v_pk_add_f32 v[92:93], v[92:93], v[176:177] neg_lo:[0,1] neg_hi:[0,1]
	v_pk_add_f32 v[94:95], v[94:95], v[176:177] neg_lo:[0,1] neg_hi:[0,1]
	v_exp_f32_e32 v32, v32
	v_exp_f32_e32 v33, v33
	v_exp_f32_e32 v34, v34
	v_exp_f32_e32 v35, v35
	v_exp_f32_e32 v36, v36
	v_exp_f32_e32 v37, v37
	v_pk_add_f32 v[178:179], v[32:33], v[34:35]
	v_exp_f32_e32 v38, v38
	v_exp_f32_e32 v39, v39
	v_pk_add_f32 v[178:179], v[178:179], v[36:37]
	v_exp_f32_e32 v40, v40
	v_exp_f32_e32 v41, v41
	v_pk_add_f32 v[178:179], v[178:179], v[38:39]
	v_exp_f32_e32 v42, v42
	v_exp_f32_e32 v43, v43
	v_pk_add_f32 v[178:179], v[178:179], v[40:41]
	v_exp_f32_e32 v44, v44
	v_exp_f32_e32 v45, v45
	v_pk_add_f32 v[178:179], v[178:179], v[42:43]
	v_exp_f32_e32 v46, v46
	v_exp_f32_e32 v47, v47
	v_pk_add_f32 v[178:179], v[178:179], v[44:45]
	v_exp_f32_e32 v48, v48
	v_exp_f32_e32 v49, v49
	v_pk_add_f32 v[178:179], v[178:179], v[46:47]
	v_exp_f32_e32 v50, v50
	v_exp_f32_e32 v51, v51
	v_pk_add_f32 v[178:179], v[178:179], v[48:49]
	v_exp_f32_e32 v52, v52
	v_exp_f32_e32 v53, v53
	v_pk_add_f32 v[178:179], v[178:179], v[50:51]
	v_exp_f32_e32 v54, v54
	v_exp_f32_e32 v55, v55
	v_pk_add_f32 v[178:179], v[178:179], v[52:53]
	v_exp_f32_e32 v56, v56
	v_exp_f32_e32 v57, v57
	v_pk_add_f32 v[178:179], v[178:179], v[54:55]
	v_exp_f32_e32 v58, v58
	v_exp_f32_e32 v59, v59
	v_pk_add_f32 v[178:179], v[178:179], v[56:57]
	v_exp_f32_e32 v60, v60
	v_exp_f32_e32 v61, v61
	v_pk_add_f32 v[178:179], v[178:179], v[58:59]
	v_exp_f32_e32 v62, v62
	v_exp_f32_e32 v63, v63
	v_pk_add_f32 v[178:179], v[178:179], v[60:61]
	v_exp_f32_e32 v64, v64
	v_exp_f32_e32 v65, v65
	v_pk_add_f32 v[178:179], v[178:179], v[62:63]
	v_exp_f32_e32 v66, v66
	v_exp_f32_e32 v67, v67
	v_pk_add_f32 v[178:179], v[178:179], v[64:65]
	v_exp_f32_e32 v68, v68
	v_exp_f32_e32 v69, v69
	v_pk_add_f32 v[178:179], v[178:179], v[66:67]
	v_exp_f32_e32 v70, v70
	v_exp_f32_e32 v71, v71
	v_pk_add_f32 v[178:179], v[178:179], v[68:69]
	v_exp_f32_e32 v72, v72
	v_exp_f32_e32 v73, v73
	v_pk_add_f32 v[178:179], v[178:179], v[70:71]
	v_exp_f32_e32 v74, v74
	v_exp_f32_e32 v75, v75
	v_pk_add_f32 v[178:179], v[178:179], v[72:73]
	v_exp_f32_e32 v76, v76
	v_exp_f32_e32 v77, v77
	v_pk_add_f32 v[178:179], v[178:179], v[74:75]
; __device__ __forceinline__ void phase_attn(KP kp, int l, unsigned char* shm) {
;     ...
;       float sum = 0.f;
; #pragma unroll
;       for (int kb = 0; kb < 16; ++kb)
; #pragma unroll
;         for (int j = 0; j < 4; ++j) { lg[kb][j] = __builtin_amdgcn_exp2f(lg[kb][j] - mx); sum += lg[kb][j]; }
;       sum += __shfl_xor(sum, 16);
;       sum += __shfl_xor(sum, 32);
;       const float inv = 1.f / sum;
;       bf16x8 pf[8];
; #pragma unroll
;       for (int s8 = 0; s8 < 8; ++s8) {
;         u32x4 pk;
;         pk[0] = cvt_pk_bf16(lg[2 * s8][0], lg[2 * s8][1]);
;         pk[1] = cvt_pk_bf16(lg[2 * s8][2], lg[2 * s8][3]);
;         pk[2] = cvt_pk_bf16(lg[2 * s8 + 1][0], lg[2 * s8 + 1][1]);
;         pk[3] = cvt_pk_bf16(lg[2 * s8 + 1][2], lg[2 * s8 + 1][3]);
;         pf[s8] = __builtin_bit_cast(bf16x8, pk);
;       }
;       f32x4 oacc[4];
; #pragma unroll
;       for (int c = 0; c < 4; ++c) oacc[c] = (f32x4){0.f, 0.f, 0.f, 0.f};
;       for (int repV = 0; repV < ((PROBE & 256) ? 2 : 1); ++repV)
;       {
;         if (repV) {
; #pragma unroll
;           for (int c = 0; c < 4; ++c) oacc[c] = (f32x4){0.f, 0.f, 0.f, 0.f};
;         }
; #pragma unroll
;         for (int i = 16; i < 32; ++i) {
;           const int idx = selw[i * 8 + ks8];
;           vr[i] = *(const u32x4*)(vbase + (size_t)idx * 128 + kvh * 64 + dc * 8);
;         }
; #pragma unroll
;         for (int s8 = 0; s8 < 8; ++s8) {
; #pragma unroll
;           for (int it = 0; it < 4; ++it) *(u32x4*)(tileb + (it * 8 + ks8) * 144 + dc * 16) = vr[s8 * 4 + it];
;           u32x2 t0, t1, t2, t3, t4, t5, t6, t7;
;           asm volatile(
;               "ds_read_b64_tr_b16 %0, %8\n\tds_read_b64_tr_b16 %1, %8 offset:2304\n\t"
;               "ds_read_b64_tr_b16 %2, %8 offset:32\n\tds_read_b64_tr_b16 %3, %8 offset:2336\n\t"
;               "ds_read_b64_tr_b16 %4, %8 offset:64\n\tds_read_b64_tr_b16 %5, %8 offset:2368\n\t"
;               "ds_read_b64_tr_b16 %6, %8 offset:96\n\tds_read_b64_tr_b16 %7, %8 offset:2400\n\t"
;               "s_waitcnt lgkmcnt(0)"
;               : "=&v"(t0), "=&v"(t1), "=&v"(t2), "=&v"(t3), "=&v"(t4), "=&v"(t5), "=&v"(t6), "=&v"(t7)
;               : "v"(tr_addr)
;               : "memory");
;           const bf16x8 a0 = __builtin_bit_cast(bf16x8, (u32x4){t0[0], t0[1], t1[0], t1[1]});
;           const bf16x8 a1 = __builtin_bit_cast(bf16x8, (u32x4){t2[0], t2[1], t3[0], t3[1]});
	v_exp_f32_e32 v78, v78
	v_exp_f32_e32 v79, v79
	v_pk_add_f32 v[178:179], v[178:179], v[76:77]
	v_exp_f32_e32 v80, v80
	v_exp_f32_e32 v81, v81
	v_pk_add_f32 v[178:179], v[178:179], v[78:79]
	v_exp_f32_e32 v82, v82
	v_exp_f32_e32 v83, v83
	v_pk_add_f32 v[178:179], v[178:179], v[80:81]
	v_exp_f32_e32 v84, v84
	v_exp_f32_e32 v85, v85
	v_pk_add_f32 v[178:179], v[178:179], v[82:83]
	v_exp_f32_e32 v86, v86
	v_exp_f32_e32 v87, v87
	v_pk_add_f32 v[178:179], v[178:179], v[84:85]
	v_exp_f32_e32 v88, v88
	v_exp_f32_e32 v89, v89
	v_pk_add_f32 v[178:179], v[178:179], v[86:87]
	v_exp_f32_e32 v90, v90
	v_exp_f32_e32 v91, v91
	v_pk_add_f32 v[178:179], v[178:179], v[88:89]
	v_exp_f32_e32 v92, v92
	v_exp_f32_e32 v93, v93
	v_pk_add_f32 v[178:179], v[178:179], v[90:91]
	v_exp_f32_e32 v94, v94
	v_exp_f32_e32 v95, v95
	v_pk_add_f32 v[178:179], v[178:179], v[92:93]
	s_nop 0
	v_pk_add_f32 v[178:179], v[178:179], v[94:95]
	v_add_f32_e32 v210, v178, v179
	ds_bpermute_b32 v197, v191, v210
	v_cvt_pk_bf16_f32 v96, v32, v33
	v_cvt_pk_bf16_f32 v97, v34, v35
	v_cvt_pk_bf16_f32 v98, v36, v37
	v_cvt_pk_bf16_f32 v99, v38, v39
	v_cvt_pk_bf16_f32 v100, v40, v41
	v_cvt_pk_bf16_f32 v101, v42, v43
	v_cvt_pk_bf16_f32 v102, v44, v45
	v_cvt_pk_bf16_f32 v103, v46, v47
	v_cvt_pk_bf16_f32 v104, v48, v49
	v_cvt_pk_bf16_f32 v105, v50, v51
	v_cvt_pk_bf16_f32 v106, v52, v53
	v_cvt_pk_bf16_f32 v107, v54, v55
	v_cvt_pk_bf16_f32 v108, v56, v57
	v_cvt_pk_bf16_f32 v109, v58, v59
	v_cvt_pk_bf16_f32 v110, v60, v61
	v_cvt_pk_bf16_f32 v111, v62, v63
	s_waitcnt lgkmcnt(0)
	v_add_f32_e32 v210, v210, v197
	ds_bpermute_b32 v197, v192, v210
	v_cvt_pk_bf16_f32 v112, v64, v65
	v_cvt_pk_bf16_f32 v113, v66, v67
	v_cvt_pk_bf16_f32 v114, v68, v69
	v_cvt_pk_bf16_f32 v115, v70, v71
	v_cvt_pk_bf16_f32 v116, v72, v73
	v_cvt_pk_bf16_f32 v117, v74, v75
	v_cvt_pk_bf16_f32 v118, v76, v77
	v_cvt_pk_bf16_f32 v119, v78, v79
	v_cvt_pk_bf16_f32 v120, v80, v81
	v_cvt_pk_bf16_f32 v121, v82, v83
	v_cvt_pk_bf16_f32 v122, v84, v85
	v_cvt_pk_bf16_f32 v123, v86, v87
	v_cvt_pk_bf16_f32 v124, v88, v89
	v_cvt_pk_bf16_f32 v125, v90, v91
	v_cvt_pk_bf16_f32 v126, v92, v93
	v_cvt_pk_bf16_f32 v127, v94, v95
	s_waitcnt lgkmcnt(0)
	v_add_f32_e32 v210, v210, v197
	v_rcp_f32_e32 v208, v210
	s_waitcnt vmcnt(8)
	ds_read_b64_tr_b16 v[160:161], v182 offset:0
	ds_read_b64_tr_b16 v[162:163], v182 offset:2048
	ds_read_b64_tr_b16 v[164:165], v183 offset:0
	ds_read_b64_tr_b16 v[166:167], v183 offset:2048
	ds_read_b64_tr_b16 v[168:169], v184 offset:0
	ds_read_b64_tr_b16 v[170:171], v184 offset:2048
	ds_read_b64_tr_b16 v[172:173], v185 offset:0
	ds_read_b64_tr_b16 v[174:175], v185 offset:2048
	s_mov_b32 m0, s49
	s_nop 0
	global_load_lds_dwordx4 v12, s[22:23]
	global_load_lds_dwordx4 v13, s[22:23] offset:1024
	global_load_lds_dwordx4 v14, s[22:23] offset:2048
	global_load_lds_dwordx4 v15, s[22:23] offset:3072
	s_waitcnt lgkmcnt(0)
	v_mfma_f32_16x16x32_bf16 v[128:131], v[160:163], v[96:99], 0
	v_mfma_f32_16x16x32_bf16 v[132:135], v[164:167], v[96:99], 0
	v_mfma_f32_16x16x32_bf16 v[136:139], v[168:171], v[96:99], 0
	v_mfma_f32_16x16x32_bf16 v[140:143], v[172:175], v[96:99], 0
	s_waitcnt vmcnt(8)
	ds_read_b64_tr_b16 v[160:161], v182 offset:4096
	ds_read_b64_tr_b16 v[162:163], v182 offset:6144
	ds_read_b64_tr_b16 v[164:165], v183 offset:4096
	ds_read_b64_tr_b16 v[166:167], v183 offset:6144
	ds_read_b64_tr_b16 v[168:169], v184 offset:4096
	ds_read_b64_tr_b16 v[170:171], v184 offset:6144
	ds_read_b64_tr_b16 v[172:173], v185 offset:4096
	ds_read_b64_tr_b16 v[174:175], v185 offset:6144
	s_mov_b32 m0, s46
	s_nop 0
	global_load_lds_dwordx4 v16, s[22:23]
	global_load_lds_dwordx4 v18, s[22:23] offset:1024
	global_load_lds_dwordx4 v19, s[22:23] offset:2048
	global_load_lds_dwordx4 v20, s[22:23] offset:3072
	s_waitcnt lgkmcnt(0)
	v_mfma_f32_16x16x32_bf16 v[128:131], v[160:163], v[100:103], v[128:131]
	v_mfma_f32_16x16x32_bf16 v[132:135], v[164:167], v[100:103], v[132:135]
	v_mfma_f32_16x16x32_bf16 v[136:139], v[168:171], v[100:103], v[136:139]
	v_mfma_f32_16x16x32_bf16 v[140:143], v[172:175], v[100:103], v[140:143]
	s_waitcnt vmcnt(8)
	ds_read_b64_tr_b16 v[160:161], v182 offset:8192
	ds_read_b64_tr_b16 v[162:163], v182 offset:10240
	ds_read_b64_tr_b16 v[164:165], v183 offset:8192
	ds_read_b64_tr_b16 v[166:167], v183 offset:10240
	ds_read_b64_tr_b16 v[168:169], v184 offset:8192
	ds_read_b64_tr_b16 v[170:171], v184 offset:10240
	ds_read_b64_tr_b16 v[172:173], v185 offset:8192
	ds_read_b64_tr_b16 v[174:175], v185 offset:10240
	s_mov_b32 m0, s47
	s_nop 0
	global_load_lds_dwordx4 v21, s[22:23]
	global_load_lds_dwordx4 v22, s[22:23] offset:1024
	global_load_lds_dwordx4 v23, s[22:23] offset:2048
	global_load_lds_dwordx4 v24, s[22:23] offset:3072
	s_waitcnt lgkmcnt(0)
	v_mfma_f32_16x16x32_bf16 v[128:131], v[160:163], v[104:107], v[128:131]
	v_mfma_f32_16x16x32_bf16 v[132:135], v[164:167], v[104:107], v[132:135]
	v_mfma_f32_16x16x32_bf16 v[136:139], v[168:171], v[104:107], v[136:139]
	v_mfma_f32_16x16x32_bf16 v[140:143], v[172:175], v[104:107], v[140:143]
	s_waitcnt vmcnt(8)
	ds_read_b64_tr_b16 v[160:161], v182 offset:12288
	ds_read_b64_tr_b16 v[162:163], v182 offset:14336
	ds_read_b64_tr_b16 v[164:165], v183 offset:12288
	ds_read_b64_tr_b16 v[166:167], v183 offset:14336
	ds_read_b64_tr_b16 v[168:169], v184 offset:12288
	ds_read_b64_tr_b16 v[170:171], v184 offset:14336
	ds_read_b64_tr_b16 v[172:173], v185 offset:12288
	ds_read_b64_tr_b16 v[174:175], v185 offset:14336
	s_mov_b32 m0, s48
	s_nop 0
	global_load_lds_dwordx4 v25, s[22:23]
	global_load_lds_dwordx4 v26, s[22:23] offset:1024
	global_load_lds_dwordx4 v27, s[22:23] offset:2048
	global_load_lds_dwordx4 v28, s[22:23] offset:3072
	s_waitcnt lgkmcnt(0)
; __device__ __forceinline__ void phase_attn(KP kp, int l, unsigned char* shm) {
;     ...
;   for (int q = blockIdx.x * 8 + w; q < MT; q += gridDim.x * 8) {
;     int r = q;
;     if (gridDim.x == 256 && q < MP) r = ((q >> 3) & 7) * 4096 + (q >> 11) * 256 + ((q >> 6) & 31) * 8 + (q & 7);
;     ...
;           oacc[0] = __builtin_amdgcn_mfma_f32_16x16x32_bf16(a0, pf[s8], oacc[0], 0, 0, 0);
;           oacc[1] = __builtin_amdgcn_mfma_f32_16x16x32_bf16(a1, pf[s8], oacc[1], 0, 0, 0);
;           oacc[2] = __builtin_amdgcn_mfma_f32_16x16x32_bf16(a2, pf[s8], oacc[2], 0, 0, 0);
;           oacc[3] = __builtin_amdgcn_mfma_f32_16x16x32_bf16(a3, pf[s8], oacc[3], 0, 0, 0);
;           if (kvh == 0 && s8 == 3) {
; #pragma unroll
;             for (int k8 = 0; k8 < 8; ++k8) {
;               const int idx = selw[k8 * 16 + nn];
;               const bf16_t* kp = kbase + (size_t)idx * 128 + 64 + kg * 8;
;               kpre[k8][0] = *(const bf16x8*)kp;
;               kpre[k8][1] = *(const bf16x8*)(kp + 32);
;             }
;           }
;         }
;         __builtin_amdgcn_sched_barrier(0);
;       }
;       if (nn < 4) {
; #pragma unroll
;         for (int c = 0; c < 4; ++c) {
;           u32x2 ow;
;           ow[0] = cvt_pk_bf16(oacc[c][0] * inv, oacc[c][1] * inv);
;           ow[1] = cvt_pk_bf16(oacc[c][2] * inv, oacc[c][3] * inv);
;           *(u32x2*)((bf16_t*)(ws + W_OA) + (size_t)r * 512 + (kvh * 4 + nn) * 64 + 16 * c + 4 * kg) = ow;
	v_mfma_f32_16x16x32_bf16 v[128:131], v[160:163], v[108:111], v[128:131]
	v_mfma_f32_16x16x32_bf16 v[132:135], v[164:167], v[108:111], v[132:135]
	v_mfma_f32_16x16x32_bf16 v[136:139], v[168:171], v[108:111], v[136:139]
	v_mfma_f32_16x16x32_bf16 v[140:143], v[172:175], v[108:111], v[140:143]
	s_waitcnt vmcnt(8)
	ds_read_b64_tr_b16 v[160:161], v182 offset:0
	ds_read_b64_tr_b16 v[162:163], v182 offset:2048
	ds_read_b64_tr_b16 v[164:165], v183 offset:0
	ds_read_b64_tr_b16 v[166:167], v183 offset:2048
	ds_read_b64_tr_b16 v[168:169], v184 offset:0
	ds_read_b64_tr_b16 v[170:171], v184 offset:2048
	ds_read_b64_tr_b16 v[172:173], v185 offset:0
	ds_read_b64_tr_b16 v[174:175], v185 offset:2048
	s_mov_b32 m0, s49
	s_nop 0
	global_load_lds_dwordx4 v29, s[22:23]
	global_load_lds_dwordx4 v30, s[22:23] offset:1024
	global_load_lds_dwordx4 v31, s[22:23] offset:2048
	global_load_lds_dwordx4 v219, s[22:23] offset:3072
	s_waitcnt lgkmcnt(0)
	v_mfma_f32_16x16x32_bf16 v[128:131], v[160:163], v[112:115], v[128:131]
	v_mfma_f32_16x16x32_bf16 v[132:135], v[164:167], v[112:115], v[132:135]
	v_mfma_f32_16x16x32_bf16 v[136:139], v[168:171], v[112:115], v[136:139]
	v_mfma_f32_16x16x32_bf16 v[140:143], v[172:175], v[112:115], v[140:143]
	s_waitcnt vmcnt(8)
	ds_read_b64_tr_b16 v[160:161], v182 offset:4096
	ds_read_b64_tr_b16 v[162:163], v182 offset:6144
	ds_read_b64_tr_b16 v[164:165], v183 offset:4096
	ds_read_b64_tr_b16 v[166:167], v183 offset:6144
	ds_read_b64_tr_b16 v[168:169], v184 offset:4096
	ds_read_b64_tr_b16 v[170:171], v184 offset:6144
	ds_read_b64_tr_b16 v[172:173], v185 offset:4096
	ds_read_b64_tr_b16 v[174:175], v185 offset:6144
	s_mov_b32 m0, s46
	s_nop 0
	global_load_lds_dwordx4 v0, s[24:25]
	global_load_lds_dwordx4 v1, s[24:25] offset:1024
	global_load_lds_dwordx4 v2, s[24:25] offset:2048
	global_load_lds_dwordx4 v3, s[24:25] offset:3072
	s_waitcnt lgkmcnt(0)
	v_mfma_f32_16x16x32_bf16 v[128:131], v[160:163], v[116:119], v[128:131]
	v_mfma_f32_16x16x32_bf16 v[132:135], v[164:167], v[116:119], v[132:135]
	v_mfma_f32_16x16x32_bf16 v[136:139], v[168:171], v[116:119], v[136:139]
	v_mfma_f32_16x16x32_bf16 v[140:143], v[172:175], v[116:119], v[140:143]
	s_waitcnt vmcnt(8)
	ds_read_b64_tr_b16 v[160:161], v182 offset:8192
	ds_read_b64_tr_b16 v[162:163], v182 offset:10240
	ds_read_b64_tr_b16 v[164:165], v183 offset:8192
	ds_read_b64_tr_b16 v[166:167], v183 offset:10240
	ds_read_b64_tr_b16 v[168:169], v184 offset:8192
	ds_read_b64_tr_b16 v[170:171], v184 offset:10240
	ds_read_b64_tr_b16 v[172:173], v185 offset:8192
	ds_read_b64_tr_b16 v[174:175], v185 offset:10240
	s_mov_b32 m0, s47
	s_nop 0
	global_load_lds_dwordx4 v4, s[24:25]
	global_load_lds_dwordx4 v5, s[24:25] offset:1024
	global_load_lds_dwordx4 v6, s[24:25] offset:2048
	global_load_lds_dwordx4 v7, s[24:25] offset:3072
	s_waitcnt lgkmcnt(0)
	v_mfma_f32_16x16x32_bf16 v[128:131], v[160:163], v[120:123], v[128:131]
	v_mfma_f32_16x16x32_bf16 v[132:135], v[164:167], v[120:123], v[132:135]
	v_mfma_f32_16x16x32_bf16 v[136:139], v[168:171], v[120:123], v[136:139]
	v_mfma_f32_16x16x32_bf16 v[140:143], v[172:175], v[120:123], v[140:143]
	s_waitcnt vmcnt(8)
	ds_read_b64_tr_b16 v[160:161], v182 offset:12288
	ds_read_b64_tr_b16 v[162:163], v182 offset:14336
	ds_read_b64_tr_b16 v[164:165], v183 offset:12288
	ds_read_b64_tr_b16 v[166:167], v183 offset:14336
	ds_read_b64_tr_b16 v[168:169], v184 offset:12288
	ds_read_b64_tr_b16 v[170:171], v184 offset:14336
	ds_read_b64_tr_b16 v[172:173], v185 offset:12288
	ds_read_b64_tr_b16 v[174:175], v185 offset:14336
	s_mov_b32 m0, s48
	s_nop 0
	global_load_lds_dwordx4 v8, s[24:25]
	global_load_lds_dwordx4 v9, s[24:25] offset:1024
	global_load_lds_dwordx4 v10, s[24:25] offset:2048
	global_load_lds_dwordx4 v11, s[24:25] offset:3072
	s_waitcnt lgkmcnt(0)
	v_mfma_f32_16x16x32_bf16 v[128:131], v[160:163], v[124:127], v[128:131]
	v_mfma_f32_16x16x32_bf16 v[132:135], v[164:167], v[124:127], v[132:135]
	v_mfma_f32_16x16x32_bf16 v[136:139], v[168:171], v[124:127], v[136:139]
	v_mfma_f32_16x16x32_bf16 v[140:143], v[172:175], v[124:127], v[140:143]
	s_nop 7
	s_nop 3
	v_mul_f32_e32 v128, v208, v128
	v_mul_f32_e32 v129, v208, v129
	v_mul_f32_e32 v130, v208, v130
	v_mul_f32_e32 v131, v208, v131
	v_cvt_pk_bf16_f32 v200, v128, v129
	v_cvt_pk_bf16_f32 v201, v130, v131
	v_mul_f32_e32 v132, v208, v132
	v_mul_f32_e32 v133, v208, v133
	v_mul_f32_e32 v134, v208, v134
	v_mul_f32_e32 v135, v208, v135
	v_cvt_pk_bf16_f32 v202, v132, v133
	v_cvt_pk_bf16_f32 v203, v134, v135
	v_mul_f32_e32 v136, v208, v136
	v_mul_f32_e32 v137, v208, v137
	v_mul_f32_e32 v138, v208, v138
	v_mul_f32_e32 v139, v208, v139
	v_cvt_pk_bf16_f32 v204, v136, v137
	v_cvt_pk_bf16_f32 v205, v138, v139
	v_mul_f32_e32 v140, v208, v140
	v_mul_f32_e32 v141, v208, v141
	v_mul_f32_e32 v142, v208, v142
	v_mul_f32_e32 v143, v208, v143
	v_cvt_pk_bf16_f32 v206, v140, v141
	v_cvt_pk_bf16_f32 v207, v142, v143
	s_mov_b64 exec, s[42:43]
	global_store_dwordx2 v190, v[200:201], s[34:35] offset:0
	global_store_dwordx2 v190, v[202:203], s[34:35] offset:32
	global_store_dwordx2 v190, v[204:205], s[34:35] offset:64
	global_store_dwordx2 v190, v[206:207], s[34:35] offset:96
	s_mov_b64 exec, -1
	s_waitcnt vmcnt(12)
	ds_read_b128 v[160:163], v180 offset:0
	ds_read_b128 v[164:167], v181 offset:0
	ds_read_b128 v[168:171], v180 offset:2048
	ds_read_b128 v[172:175], v181 offset:2048
	s_add_i32 s50, s2, s4
	s_cmp_lg_u32 s5, 0
	s_cbranch_scc1 .Lattn_nq_7
	s_cmp_lt_i32 s50, 0x8000
	s_cbranch_scc1 .Lattn_nq_7
	s_lshl_b32 s6, s57, 1
	s_add_i32 s6, s6, s56
	s_add_i32 s6, s6, 0x8000
	s_cmp_lt_u32 s56, 2
	s_cselect_b32 s6, s6, 0x10000
	s_cmp_ge_i32 s2, 0x8000
	s_cselect_b32 s50, 0x10000, s6
.Lattn_nq_7:
	s_cmp_lt_i32 s50, 0x8200
	s_cselect_b32 s53, s50, s2
	s_mov_b32 s51, s53
	s_cmp_lg_u32 s5, 0
	s_cbranch_scc1 .Lattn_noswz_8
	s_cmp_ge_i32 s53, 0x8000
	s_cbranch_scc1 .Lattn_noswz_8
	s_lshl_b32 s6, s53, 9
	s_and_b32 s6, s6, 0x7000
	s_lshr_b32 s7, s53, 3
	s_and_b32 s8, s7, 0xffffff00
	s_and_b32 s7, s7, 0xf8
	s_or_b32 s6, s6, s8
	s_or_b32 s6, s6, s7
	s_and_b32 s7, s53, 7
	s_or_b32 s51, s6, s7
